# output-projection epilogue de-serialised: residual x loads issued 8 steps ahead into dead fragment registers with counted waits (was a load-wait-store ladder)
# speedup vs baseline: 1.0079x; 1.0056x over previous
;     __device__ __forceinline__ void operator()(const f32x4 (&acc)[2][2][4][2], const pg8::Unit& u, int wr, int wc, int fr, int fq) const {
;     ...
; #pragma unroll
;         for (int ai = 0; ai < 2; ++ai)
; #pragma unroll
;             for (int m = 0; m < 4; ++m) { const size_t row = (size_t)(row0 + ai * 128 + m * 16);
; #pragma unroll
;                 for (int bj = 0; bj < 2; ++bj) { const size_t off = row * 2048 + col0 + bj * 128;
;                     const f32x4 x0 = *(const f32x4*)(X + off), x1 = *(const f32x4*)(X + off + 4);
;                     *(f32x4*)(Y + off) = x0 * ALPHA + acc[ai][bj][m][0]; *(f32x4*)(Y + off + 4) = x1 * ALPHA + acc[ai][bj][m][1]; } }
.LBB0_1064:
	v_lshl_add_u32 v160, s40, 8, v146
	v_lshl_or_b32 v162, s61, 8, v148
	v_ashrrev_i32_e32 v161, 31, v160
	v_ashrrev_i32_e32 v163, 31, v162
	v_lshlrev_b64 v[144:145], 11, v[160:161]
	v_lshl_add_u64 v[144:145], v[144:145], 0, v[162:163]
	v_lshlrev_b64 v[144:145], 2, v[144:145]
	v_lshl_add_u64 v[244:245], s[36:37], 0, v[144:145]
	v_lshl_add_u64 v[246:247], s[54:55], 0, v[144:145]
	v_mov_b32_e32 v250, 0x20000
	v_mov_b32_e32 v251, 0
	v_mov_b32_e32 v248, 0xa0000
	v_mov_b32_e32 v249, 0
	s_andn2_b64 vcc, exec, s[0:1]
	s_mov_b64 s[0:1], -1
	global_load_dwordx4 v[168:171], v[244:245], off
	global_load_dwordx4 v[172:175], v[244:245], off offset:16
	global_load_dwordx4 v[176:179], v[244:245], off offset:512
	global_load_dwordx4 v[180:183], v[244:245], off offset:528
	v_lshl_add_u64 v[244:245], v[244:245], 0, v[250:251]
	global_load_dwordx4 v[184:187], v[244:245], off
	global_load_dwordx4 v[190:193], v[244:245], off offset:16
	global_load_dwordx4 v[194:197], v[244:245], off offset:512
	global_load_dwordx4 v[198:201], v[244:245], off offset:528
	v_lshl_add_u64 v[244:245], v[244:245], 0, v[250:251]
	global_load_dwordx4 v[202:205], v[244:245], off
	global_load_dwordx4 v[208:211], v[244:245], off offset:16
	global_load_dwordx4 v[212:215], v[244:245], off offset:512
	global_load_dwordx4 v[216:219], v[244:245], off offset:528
	v_lshl_add_u64 v[244:245], v[244:245], 0, v[250:251]
	global_load_dwordx4 v[228:231], v[244:245], off
	global_load_dwordx4 v[232:235], v[244:245], off offset:16
	global_load_dwordx4 v[236:239], v[244:245], off offset:512
	global_load_dwordx4 v[240:243], v[244:245], off offset:528
	v_lshl_add_u64 v[244:245], v[244:245], 0, v[248:249]
	s_waitcnt vmcnt(14)
	v_pk_fma_f32 v[124:125], v[168:169], s[12:13], v[124:125] op_sel_hi:[1,0,1]
	v_pk_fma_f32 v[126:127], v[170:171], s[12:13], v[126:127] op_sel_hi:[1,0,1]
	v_pk_fma_f32 v[120:121], v[172:173], s[12:13], v[120:121] op_sel_hi:[1,0,1]
	v_pk_fma_f32 v[122:123], v[174:175], s[12:13], v[122:123] op_sel_hi:[1,0,1]
	global_store_dwordx4 v[246:247], v[124:127], off
	global_store_dwordx4 v[246:247], v[120:123], off offset:16
	global_load_dwordx4 v[168:171], v[244:245], off
	global_load_dwordx4 v[172:175], v[244:245], off offset:16
	s_waitcnt vmcnt(16)
	v_pk_fma_f32 v[112:113], v[176:177], s[12:13], v[112:113] op_sel_hi:[1,0,1]
	v_pk_fma_f32 v[114:115], v[178:179], s[12:13], v[114:115] op_sel_hi:[1,0,1]
	v_pk_fma_f32 v[108:109], v[180:181], s[12:13], v[108:109] op_sel_hi:[1,0,1]
	v_pk_fma_f32 v[110:111], v[182:183], s[12:13], v[110:111] op_sel_hi:[1,0,1]
	global_store_dwordx4 v[246:247], v[112:115], off offset:512
	global_store_dwordx4 v[246:247], v[108:111], off offset:528
	v_lshl_add_u64 v[246:247], v[246:247], 0, v[250:251]
	global_load_dwordx4 v[176:179], v[244:245], off offset:512
	global_load_dwordx4 v[180:183], v[244:245], off offset:528
	v_lshl_add_u64 v[244:245], v[244:245], 0, v[250:251]
	s_waitcnt vmcnt(18)
	v_pk_fma_f32 v[116:117], v[184:185], s[12:13], v[116:117] op_sel_hi:[1,0,1]
	v_pk_fma_f32 v[118:119], v[186:187], s[12:13], v[118:119] op_sel_hi:[1,0,1]
	v_pk_fma_f32 v[104:105], v[190:191], s[12:13], v[104:105] op_sel_hi:[1,0,1]
	v_pk_fma_f32 v[106:107], v[192:193], s[12:13], v[106:107] op_sel_hi:[1,0,1]
	global_store_dwordx4 v[246:247], v[116:119], off
	global_store_dwordx4 v[246:247], v[104:107], off offset:16
	global_load_dwordx4 v[184:187], v[244:245], off
	global_load_dwordx4 v[190:193], v[244:245], off offset:16
	s_waitcnt vmcnt(20)
	v_pk_fma_f32 v[96:97], v[194:195], s[12:13], v[96:97] op_sel_hi:[1,0,1]
	v_pk_fma_f32 v[98:99], v[196:197], s[12:13], v[98:99] op_sel_hi:[1,0,1]
	v_pk_fma_f32 v[92:93], v[198:199], s[12:13], v[92:93] op_sel_hi:[1,0,1]
	v_pk_fma_f32 v[94:95], v[200:201], s[12:13], v[94:95] op_sel_hi:[1,0,1]
	global_store_dwordx4 v[246:247], v[96:99], off offset:512
	global_store_dwordx4 v[246:247], v[92:95], off offset:528
	v_lshl_add_u64 v[246:247], v[246:247], 0, v[250:251]
	global_load_dwordx4 v[194:197], v[244:245], off offset:512
	global_load_dwordx4 v[198:201], v[244:245], off offset:528
	v_lshl_add_u64 v[244:245], v[244:245], 0, v[250:251]
	s_waitcnt vmcnt(22)
	v_pk_fma_f32 v[100:101], v[202:203], s[12:13], v[100:101] op_sel_hi:[1,0,1]
	v_pk_fma_f32 v[102:103], v[204:205], s[12:13], v[102:103] op_sel_hi:[1,0,1]
	v_pk_fma_f32 v[88:89], v[208:209], s[12:13], v[88:89] op_sel_hi:[1,0,1]
	v_pk_fma_f32 v[90:91], v[210:211], s[12:13], v[90:91] op_sel_hi:[1,0,1]
	global_store_dwordx4 v[246:247], v[100:103], off
	global_store_dwordx4 v[246:247], v[88:91], off offset:16
	global_load_dwordx4 v[202:205], v[244:245], off
	global_load_dwordx4 v[208:211], v[244:245], off offset:16
	s_waitcnt vmcnt(24)
	v_pk_fma_f32 v[80:81], v[212:213], s[12:13], v[80:81] op_sel_hi:[1,0,1]
	v_pk_fma_f32 v[82:83], v[214:215], s[12:13], v[82:83] op_sel_hi:[1,0,1]
	v_pk_fma_f32 v[76:77], v[216:217], s[12:13], v[76:77] op_sel_hi:[1,0,1]
	v_pk_fma_f32 v[78:79], v[218:219], s[12:13], v[78:79] op_sel_hi:[1,0,1]
	global_store_dwordx4 v[246:247], v[80:83], off offset:512
	global_store_dwordx4 v[246:247], v[76:79], off offset:528
	v_lshl_add_u64 v[246:247], v[246:247], 0, v[250:251]
	global_load_dwordx4 v[212:215], v[244:245], off offset:512
	global_load_dwordx4 v[216:219], v[244:245], off offset:528
	v_lshl_add_u64 v[244:245], v[244:245], 0, v[250:251]
	s_waitcnt vmcnt(26)
;     __device__ __forceinline__ void operator()(const f32x4 (&acc)[2][2][4][2], const pg8::Unit& u, int wr, int wc, int fr, int fq) const {
;     ...
; #pragma unroll
;         for (int ai = 0; ai < 2; ++ai)
; #pragma unroll
;             for (int m = 0; m < 4; ++m) { const size_t row = (size_t)(row0 + ai * 128 + m * 16);
; #pragma unroll
;                 for (int bj = 0; bj < 2; ++bj) { const size_t off = row * 2048 + col0 + bj * 128;
;                     const f32x4 x0 = *(const f32x4*)(X + off), x1 = *(const f32x4*)(X + off + 4);
;                     *(f32x4*)(Y + off) = x0 * ALPHA + acc[ai][bj][m][0]; *(f32x4*)(Y + off + 4) = x1 * ALPHA + acc[ai][bj][m][1]; } }
	v_pk_fma_f32 v[84:85], v[228:229], s[12:13], v[84:85] op_sel_hi:[1,0,1]
	v_pk_fma_f32 v[86:87], v[230:231], s[12:13], v[86:87] op_sel_hi:[1,0,1]
	v_pk_fma_f32 v[72:73], v[232:233], s[12:13], v[72:73] op_sel_hi:[1,0,1]
	v_pk_fma_f32 v[74:75], v[234:235], s[12:13], v[74:75] op_sel_hi:[1,0,1]
	global_store_dwordx4 v[246:247], v[84:87], off
	global_store_dwordx4 v[246:247], v[72:75], off offset:16
	global_load_dwordx4 v[228:231], v[244:245], off
	global_load_dwordx4 v[232:235], v[244:245], off offset:16
	s_waitcnt vmcnt(28)
	v_pk_fma_f32 v[68:69], v[236:237], s[12:13], v[68:69] op_sel_hi:[1,0,1]
	v_pk_fma_f32 v[70:71], v[238:239], s[12:13], v[70:71] op_sel_hi:[1,0,1]
	v_pk_fma_f32 v[64:65], v[240:241], s[12:13], v[64:65] op_sel_hi:[1,0,1]
	v_pk_fma_f32 v[66:67], v[242:243], s[12:13], v[66:67] op_sel_hi:[1,0,1]
	global_store_dwordx4 v[246:247], v[68:71], off offset:512
	global_store_dwordx4 v[246:247], v[64:67], off offset:528
	v_lshl_add_u64 v[246:247], v[246:247], 0, v[248:249]
	global_load_dwordx4 v[236:239], v[244:245], off offset:512
	global_load_dwordx4 v[240:243], v[244:245], off offset:528
	v_lshl_add_u64 v[244:245], v[244:245], 0, v[250:251]
	s_waitcnt vmcnt(28)
	v_pk_fma_f32 v[60:61], v[168:169], s[12:13], v[60:61] op_sel_hi:[1,0,1]
	v_pk_fma_f32 v[62:63], v[170:171], s[12:13], v[62:63] op_sel_hi:[1,0,1]
	v_pk_fma_f32 v[56:57], v[172:173], s[12:13], v[56:57] op_sel_hi:[1,0,1]
	v_pk_fma_f32 v[58:59], v[174:175], s[12:13], v[58:59] op_sel_hi:[1,0,1]
	global_store_dwordx4 v[246:247], v[60:63], off
	global_store_dwordx4 v[246:247], v[56:59], off offset:16
	s_waitcnt vmcnt(26)
	v_pk_fma_f32 v[48:49], v[176:177], s[12:13], v[48:49] op_sel_hi:[1,0,1]
	v_pk_fma_f32 v[50:51], v[178:179], s[12:13], v[50:51] op_sel_hi:[1,0,1]
	v_pk_fma_f32 v[44:45], v[180:181], s[12:13], v[44:45] op_sel_hi:[1,0,1]
	v_pk_fma_f32 v[46:47], v[182:183], s[12:13], v[46:47] op_sel_hi:[1,0,1]
	global_store_dwordx4 v[246:247], v[48:51], off offset:512
	global_store_dwordx4 v[246:247], v[44:47], off offset:528
	v_lshl_add_u64 v[246:247], v[246:247], 0, v[250:251]
	s_waitcnt vmcnt(24)
	v_pk_fma_f32 v[52:53], v[184:185], s[12:13], v[52:53] op_sel_hi:[1,0,1]
	v_pk_fma_f32 v[54:55], v[186:187], s[12:13], v[54:55] op_sel_hi:[1,0,1]
	v_pk_fma_f32 v[40:41], v[190:191], s[12:13], v[40:41] op_sel_hi:[1,0,1]
	v_pk_fma_f32 v[42:43], v[192:193], s[12:13], v[42:43] op_sel_hi:[1,0,1]
	global_store_dwordx4 v[246:247], v[52:55], off
	global_store_dwordx4 v[246:247], v[40:43], off offset:16
	s_waitcnt vmcnt(22)
	v_pk_fma_f32 v[32:33], v[194:195], s[12:13], v[32:33] op_sel_hi:[1,0,1]
	v_pk_fma_f32 v[34:35], v[196:197], s[12:13], v[34:35] op_sel_hi:[1,0,1]
	v_pk_fma_f32 v[28:29], v[198:199], s[12:13], v[28:29] op_sel_hi:[1,0,1]
	v_pk_fma_f32 v[30:31], v[200:201], s[12:13], v[30:31] op_sel_hi:[1,0,1]
	global_store_dwordx4 v[246:247], v[32:35], off offset:512
	global_store_dwordx4 v[246:247], v[28:31], off offset:528
	v_lshl_add_u64 v[246:247], v[246:247], 0, v[250:251]
	s_waitcnt vmcnt(20)
	v_pk_fma_f32 v[36:37], v[202:203], s[12:13], v[36:37] op_sel_hi:[1,0,1]
	v_pk_fma_f32 v[38:39], v[204:205], s[12:13], v[38:39] op_sel_hi:[1,0,1]
	v_pk_fma_f32 v[24:25], v[208:209], s[12:13], v[24:25] op_sel_hi:[1,0,1]
	v_pk_fma_f32 v[26:27], v[210:211], s[12:13], v[26:27] op_sel_hi:[1,0,1]
	global_store_dwordx4 v[246:247], v[36:39], off
	global_store_dwordx4 v[246:247], v[24:27], off offset:16
	s_waitcnt vmcnt(18)
	v_pk_fma_f32 v[16:17], v[212:213], s[12:13], v[16:17] op_sel_hi:[1,0,1]
	v_pk_fma_f32 v[18:19], v[214:215], s[12:13], v[18:19] op_sel_hi:[1,0,1]
	v_pk_fma_f32 v[12:13], v[216:217], s[12:13], v[12:13] op_sel_hi:[1,0,1]
	v_pk_fma_f32 v[14:15], v[218:219], s[12:13], v[14:15] op_sel_hi:[1,0,1]
	global_store_dwordx4 v[246:247], v[16:19], off offset:512
	global_store_dwordx4 v[246:247], v[12:15], off offset:528
	v_lshl_add_u64 v[246:247], v[246:247], 0, v[250:251]
	s_waitcnt vmcnt(16)
	v_pk_fma_f32 v[20:21], v[228:229], s[12:13], v[20:21] op_sel_hi:[1,0,1]
	v_pk_fma_f32 v[22:23], v[230:231], s[12:13], v[22:23] op_sel_hi:[1,0,1]
	v_pk_fma_f32 v[8:9], v[232:233], s[12:13], v[8:9] op_sel_hi:[1,0,1]
	v_pk_fma_f32 v[10:11], v[234:235], s[12:13], v[10:11] op_sel_hi:[1,0,1]
	global_store_dwordx4 v[246:247], v[20:23], off
	global_store_dwordx4 v[246:247], v[8:11], off offset:16
	s_waitcnt vmcnt(14)
	v_pk_fma_f32 v[4:5], v[236:237], s[12:13], v[4:5] op_sel_hi:[1,0,1]
	v_pk_fma_f32 v[6:7], v[238:239], s[12:13], v[6:7] op_sel_hi:[1,0,1]
	v_pk_fma_f32 v[0:1], v[240:241], s[12:13], v[0:1] op_sel_hi:[1,0,1]
	v_pk_fma_f32 v[2:3], v[242:243], s[12:13], v[2:3] op_sel_hi:[1,0,1]
	global_store_dwordx4 v[246:247], v[4:7], off offset:512
	global_store_dwordx4 v[246:247], v[0:3], off offset:528
	v_lshl_add_u64 v[246:247], v[246:247], 0, v[250:251]
	s_nop 0
	s_nop 0
	s_nop 0
	s_nop 0
	s_cbranch_vccnz .LBB0_1053
	s_andn2_b64 vcc, exec, s[6:7]
	s_cbranch_vccnz .LBB0_1052
	s_barrier
	s_branch .LBB0_1052
